# scan step: counted LDS waits (lgkmcnt(8)) so each MFMA group waits only for the fragment group it consumes; on top of nt4
# baseline (speedup 1.0000x reference)
; #define LAS __attribute__((address_space(3)))
; #define GD_GLDS(cidx, buf) do { const unsigned char* src_ = REC + (size_t)(cidx) * GD_REC + lane * 16; \
;         _Pragma("unroll") for (int k_ = 0; k_ < 7; ++k_) __builtin_amdgcn_global_load_lds((const unsigned*)(src_ + (n + 8 * k_) * 1024), (LAS unsigned*)(lds + (buf) * GD_REC + (n + 8 * k_) * 1024), 16, 0, 0); } while (0)
; #define GD_LOAD8(dst, f0) do { _Pragma("unroll") for (int i_ = 0; i_ < 8; ++i_) dst[i_] = GD_FRAG((f0) + i_); } while (0)
; #define GD_PIN() __builtin_amdgcn_sched_barrier(0)
; __device__ __forceinline__ void gdn_scan_phase(const Frame& F0, const Args& a0, int nblk, bool last) {
;     ...
;         if (s + 1 < 36) { const int cn = GD_CHUNK(s + 1);
; #pragma unroll
;             for (int mt = 0; mt < 4; ++mt) un[mt] = *(const f32x4*)(UB + (size_t)cn * 8192 + ((mt * 8 + n) * 64 + lane) * 4);
;             gln = GLB[cn];
;             GD_GLDS(cn, (s + 1) & 1); }
;         const LAS unsigned char* Bf = lds + (s & 1) * GD_REC + lane * 16;
;     ...
;         bf16x8 fA[8], fB[8], fC[8];
;     ...
;         GD_LOAD8(fA, 0); GD_LOAD8(fB, 8);
;         bf16x8 Sf[4];
; #pragma unroll
;         for (int kb = 0; kb < 4; ++kb) Sf[kb] = pack8(S[2 * kb], S[2 * kb + 1]);
;         f32x4 O[4];
; #pragma unroll
;         for (int mt = 0; mt < 4; ++mt) O[mt] = (f32x4){0.f, 0.f, 0.f, 0.f};
;         GD_PIN();
; #pragma unroll
;         for (int i = 0; i < 8; ++i) V[i >> 2] = __builtin_amdgcn_mfma_f32_16x16x32_bf16(fA[i], Sf[i & 3], V[i >> 2], 0, 0, 0);
;         GD_PIN(); GD_LOAD8(fC, 16); GD_PIN();
; #pragma unroll
;         for (int i = 0; i < 8; ++i) V[2 + (i >> 2)] = __builtin_amdgcn_mfma_f32_16x16x32_bf16(fB[i], Sf[i & 3], V[2 + (i >> 2)], 0, 0, 0);
;         GD_PIN(); GD_LOAD8(fA, 24); GD_PIN();
; #pragma unroll
;         for (int i = 0; i < 8; ++i) O[i >> 2] = __builtin_amdgcn_mfma_f32_16x16x32_bf16(fC[i], Sf[i & 3], O[i >> 2], 0, 0, 0);
;         GD_PIN(); GD_LOAD8(fB, 32); GD_PIN();
; #pragma unroll
;         for (int i = 0; i < 8; ++i) O[2 + (i >> 2)] = __builtin_amdgcn_mfma_f32_16x16x32_bf16(fA[i], Sf[i & 3], O[2 + (i >> 2)], 0, 0, 0);
.LBB0_572:
	s_cmp_gt_u32 s8, 3
	s_cselect_b32 s7, 39, 3
	s_add_i32 s7, s7, s26
	s_sub_i32 s7, s7, 38
	s_and_b64 s[10:11], s[4:5], exec
	s_cselect_b32 s27, s8, s7
	s_ashr_i32 s7, s6, 31
	s_lshl_b64 s[10:11], s[6:7], 15
	s_add_u32 s10, s23, s10
	s_addc_u32 s11, s24, s11
	v_lshl_add_u64 v[32:33], v[70:71], 2, s[10:11]
	v_lshl_add_u64 v[34:35], v[72:73], 2, s[10:11]
	global_load_dwordx4 v[44:47], v[32:33], off nt
	global_load_dwordx4 v[40:43], v[34:35], off nt
	v_lshl_add_u64 v[32:33], v[74:75], 2, s[10:11]
	v_lshl_add_u64 v[34:35], v[76:77], 2, s[10:11]
	s_lshl_b64 s[10:11], s[6:7], 2
	s_add_u32 s10, s0, s10
	s_addc_u32 s11, s1, s11
	v_mad_i64_i32 v[104:105], s[6:7], s6, v193, v[78:79]
	s_bitcmp1_b32 s29, 0
	s_cselect_b32 s6, 0xe000, 0
	s_add_i32 s6, s25, s6
	v_lshl_add_u64 v[106:107], v[104:105], 0, s[30:31]
	s_mov_b32 m0, s6
	global_load_dwordx4 v[36:39], v[32:33], off nt
	s_nop 0
	global_load_dwordx4 v[32:35], v[34:35], off nt
	v_cvt_pk_bf16_f32 v170, v28, v29
	global_load_lds_dwordx4 v[106:107], off nt
	v_lshl_add_u64 v[106:107], v[104:105], 0, s[68:69]
	s_add_i32 m0, s6, 0x2000
	global_load_dword v103, v161, s[10:11]
	v_cvt_pk_bf16_f32 v171, v30, v31
	global_load_lds_dwordx4 v[106:107], off nt
	v_lshl_add_u64 v[106:107], v[104:105], 0, s[70:71]
	s_add_i32 m0, s6, 0x4000
	v_cvt_pk_bf16_f32 v172, v24, v25
	global_load_lds_dwordx4 v[106:107], off nt
	v_lshl_add_u64 v[106:107], v[104:105], 0, s[74:75]
	s_add_i32 m0, s6, 0x6000
	v_cvt_pk_bf16_f32 v173, v26, v27
	global_load_lds_dwordx4 v[106:107], off nt
	v_lshl_add_u64 v[106:107], v[104:105], 0, s[78:79]
	s_add_i32 m0, s6, 0x8000
	v_cvt_pk_bf16_f32 v174, v20, v21
	global_load_lds_dwordx4 v[106:107], off nt
	v_lshl_add_u64 v[106:107], v[104:105], 0, s[82:83]
	s_add_i32 m0, s6, 0xa000
	v_lshl_add_u64 v[104:105], v[104:105], 0, s[88:89]
	global_load_lds_dwordx4 v[106:107], off nt
	s_add_i32 m0, s6, 0xc000
	s_and_b32 s6, s8, 1
	global_load_lds_dwordx4 v[104:105], off nt
	s_mul_i32 s7, s6, 0xe000
	v_add_u32_e32 v160, s7, v101
	ds_read_b128 v[104:107], v160
	ds_read_b128 v[108:111], v160 offset:1024
	ds_read_b128 v[112:115], v160 offset:2048
	ds_read_b128 v[116:119], v160 offset:3072
	ds_read_b128 v[120:123], v160 offset:4096
	ds_read_b128 v[124:127], v160 offset:5120
	ds_read_b128 v[128:131], v160 offset:6144
	ds_read_b128 v[132:135], v160 offset:7168
	ds_read_b128 v[136:139], v160 offset:8192
	ds_read_b128 v[140:143], v160 offset:9216
	ds_read_b128 v[144:147], v160 offset:10240
	ds_read_b128 v[148:151], v160 offset:11264
	ds_read_b128 v[152:155], v160 offset:12288
	ds_read_b128 v[156:159], v160 offset:13312
	ds_read_b128 v[162:165], v160 offset:14336
	ds_read_b128 v[166:169], v160 offset:15360
	v_cvt_pk_bf16_f32 v175, v22, v23
	v_cvt_pk_bf16_f32 v176, v16, v17
	v_cvt_pk_bf16_f32 v177, v18, v19
	v_cvt_pk_bf16_f32 v178, v12, v13
	v_cvt_pk_bf16_f32 v179, v14, v15
	v_cvt_pk_bf16_f32 v180, v8, v9
	v_cvt_pk_bf16_f32 v181, v10, v11
	v_cvt_pk_bf16_f32 v196, v4, v5
	v_cvt_pk_bf16_f32 v197, v6, v7
	v_cvt_pk_bf16_f32 v198, v0, v1
	v_cvt_pk_bf16_f32 v199, v2, v3
	s_waitcnt lgkmcnt(8)
	v_mfma_f32_16x16x32_bf16 v[60:63], v[104:107], v[170:173], v[60:63]
	v_mfma_f32_16x16x32_bf16 v[56:59], v[120:123], v[170:173], v[56:59]
	v_mfma_f32_16x16x32_bf16 v[60:63], v[108:111], v[174:177], v[60:63]
	v_mfma_f32_16x16x32_bf16 v[56:59], v[124:127], v[174:177], v[56:59]
	v_mfma_f32_16x16x32_bf16 v[60:63], v[112:115], v[178:181], v[60:63]
	v_mfma_f32_16x16x32_bf16 v[56:59], v[128:131], v[178:181], v[56:59]
	v_mfma_f32_16x16x32_bf16 v[60:63], v[116:119], v[196:199], v[60:63]
	v_mfma_f32_16x16x32_bf16 v[56:59], v[132:135], v[196:199], v[56:59]
	ds_read_b128 v[104:107], v160 offset:16384
	ds_read_b128 v[108:111], v160 offset:17408
	ds_read_b128 v[112:115], v160 offset:18432
	ds_read_b128 v[116:119], v160 offset:19456
	ds_read_b128 v[120:123], v160 offset:20480
	ds_read_b128 v[124:127], v160 offset:21504
	ds_read_b128 v[128:131], v160 offset:22528
	ds_read_b128 v[132:135], v160 offset:23552
	s_waitcnt lgkmcnt(8)
	v_mfma_f32_16x16x32_bf16 v[52:55], v[136:139], v[170:173], v[52:55]
	v_mfma_f32_16x16x32_bf16 v[48:51], v[152:155], v[170:173], v[48:51]
	v_mfma_f32_16x16x32_bf16 v[52:55], v[140:143], v[174:177], v[52:55]
	v_mfma_f32_16x16x32_bf16 v[48:51], v[156:159], v[174:177], v[48:51]
	v_mfma_f32_16x16x32_bf16 v[52:55], v[144:147], v[178:181], v[52:55]
	v_mfma_f32_16x16x32_bf16 v[48:51], v[162:165], v[178:181], v[48:51]
	v_mfma_f32_16x16x32_bf16 v[52:55], v[148:151], v[196:199], v[52:55]
	v_mfma_f32_16x16x32_bf16 v[48:51], v[166:169], v[196:199], v[48:51]
	ds_read_b128 v[136:139], v160 offset:24576
	ds_read_b128 v[140:143], v160 offset:25600
	ds_read_b128 v[144:147], v160 offset:26624
	ds_read_b128 v[148:151], v160 offset:27648
	ds_read_b128 v[152:155], v160 offset:28672
	ds_read_b128 v[156:159], v160 offset:29696
	ds_read_b128 v[162:165], v160 offset:30720
	ds_read_b128 v[166:169], v160 offset:31744
	s_waitcnt lgkmcnt(8)
	v_mfma_f32_16x16x32_bf16 v[104:107], v[104:107], v[170:173], 0
	v_mfma_f32_16x16x32_bf16 v[104:107], v[108:111], v[174:177], v[104:107]
	v_mfma_f32_16x16x32_bf16 v[108:111], v[120:123], v[170:173], 0
	v_mfma_f32_16x16x32_bf16 v[108:111], v[124:127], v[174:177], v[108:111]
	v_mfma_f32_16x16x32_bf16 v[104:107], v[112:115], v[178:181], v[104:107]
	v_mfma_f32_16x16x32_bf16 v[108:111], v[128:131], v[178:181], v[108:111]
	v_mfma_f32_16x16x32_bf16 v[104:107], v[116:119], v[196:199], v[104:107]
	v_mfma_f32_16x16x32_bf16 v[108:111], v[132:135], v[196:199], v[108:111]
	ds_read_b128 v[112:115], v160 offset:32768
	ds_read_b128 v[116:119], v160 offset:33792
	ds_read_b128 v[120:123], v160 offset:34816
	ds_read_b128 v[124:127], v160 offset:35840
	ds_read_b128 v[128:131], v160 offset:36864
	ds_read_b128 v[132:135], v160 offset:37888
	ds_read_b128 v[200:203], v160 offset:38912
	ds_read_b128 v[204:207], v160 offset:39936
	s_waitcnt lgkmcnt(8)
; #define GD_LOAD8(dst, f0) do { _Pragma("unroll") for (int i_ = 0; i_ < 8; ++i_) dst[i_] = GD_FRAG((f0) + i_); } while (0)
; #define GD_PIN() __builtin_amdgcn_sched_barrier(0)
; __device__ __forceinline__ void gdn_scan_phase(const Frame& F0, const Args& a0, int nblk, bool last) {
;     ...
;         GD_PIN(); GD_LOAD8(fB, 32); GD_PIN();
; #pragma unroll
;         for (int i = 0; i < 8; ++i) O[2 + (i >> 2)] = __builtin_amdgcn_mfma_f32_16x16x32_bf16(fA[i], Sf[i & 3], O[2 + (i >> 2)], 0, 0, 0);
;         GD_PIN(); GD_LOAD8(fC, 40); GD_PIN();
;         bf16x8 Vf[2]; Vf[0] = pack8(V[0], V[1]); Vf[1] = pack8(V[2], V[3]);
; #pragma unroll
;         for (int t = 0; t < 8; ++t) S[t] = S[t] * gl;
; #pragma unroll
;         for (int i = 0; i < 8; ++i) S[i >> 1] = __builtin_amdgcn_mfma_f32_16x16x32_bf16(fB[i], Vf[i & 1], S[i >> 1], 0, 0, 0);
;         GD_PIN();
; #pragma unroll
;         for (int i_ = 0; i_ < 8; ++i_) if (i_ != 1 && i_ != 3) fA[i_] = GD_FRAG(48 + i_);
;         GD_PIN();
; #pragma unroll
;         for (int i = 0; i < 8; ++i) S[4 + (i >> 1)] = __builtin_amdgcn_mfma_f32_16x16x32_bf16(fC[i], Vf[i & 1], S[4 + (i >> 1)], 0, 0, 0);
; #pragma unroll
;         for (int i = 0; i < 8; ++i) if (i != 1 && i != 3) O[i >> 1] = __builtin_amdgcn_mfma_f32_16x16x32_bf16(fA[i], Vf[i & 1], O[i >> 1], 0, 0, 0);
	v_mfma_f32_16x16x32_bf16 v[136:139], v[136:139], v[170:173], 0
	v_mfma_f32_16x16x32_bf16 v[136:139], v[140:143], v[174:177], v[136:139]
	v_mfma_f32_16x16x32_bf16 v[140:143], v[152:155], v[170:173], 0
	v_mfma_f32_16x16x32_bf16 v[140:143], v[156:159], v[174:177], v[140:143]
	v_mfma_f32_16x16x32_bf16 v[136:139], v[144:147], v[178:181], v[136:139]
	v_mfma_f32_16x16x32_bf16 v[140:143], v[162:165], v[178:181], v[140:143]
	v_mfma_f32_16x16x32_bf16 v[136:139], v[148:151], v[196:199], v[136:139]
	v_mfma_f32_16x16x32_bf16 v[140:143], v[166:169], v[196:199], v[140:143]
	ds_read_b128 v[144:147], v160 offset:40960
	ds_read_b128 v[148:151], v160 offset:41984
	ds_read_b128 v[152:155], v160 offset:43008
	ds_read_b128 v[156:159], v160 offset:44032
	ds_read_b128 v[162:165], v160 offset:45056
	ds_read_b128 v[166:169], v160 offset:46080
	ds_read_b128 v[170:173], v160 offset:47104
	ds_read_b128 v[174:177], v160 offset:48128
	v_cvt_pk_bf16_f32 v178, v60, v61
	v_cvt_pk_bf16_f32 v179, v62, v63
	v_cvt_pk_bf16_f32 v180, v56, v57
	v_cvt_pk_bf16_f32 v181, v58, v59
	v_pk_mul_f32 v[30:31], v[30:31], v[80:81] op_sel_hi:[1,0]
	v_pk_mul_f32 v[28:29], v[28:29], v[80:81] op_sel_hi:[1,0]
	v_pk_mul_f32 v[26:27], v[26:27], v[80:81] op_sel_hi:[1,0]
	v_pk_mul_f32 v[24:25], v[24:25], v[80:81] op_sel_hi:[1,0]
	v_pk_mul_f32 v[22:23], v[22:23], v[80:81] op_sel_hi:[1,0]
	v_pk_mul_f32 v[20:21], v[20:21], v[80:81] op_sel_hi:[1,0]
	v_pk_mul_f32 v[18:19], v[18:19], v[80:81] op_sel_hi:[1,0]
	v_pk_mul_f32 v[16:17], v[16:17], v[80:81] op_sel_hi:[1,0]
	s_waitcnt lgkmcnt(8)
	v_mfma_f32_16x16x32_bf16 v[28:31], v[112:115], v[178:181], v[28:31]
	v_cvt_pk_bf16_f32 v196, v52, v53
	v_cvt_pk_bf16_f32 v197, v54, v55
	v_cvt_pk_bf16_f32 v198, v48, v49
	v_mfma_f32_16x16x32_bf16 v[24:27], v[120:123], v[178:181], v[24:27]
	v_cvt_pk_bf16_f32 v199, v50, v51
	v_pk_mul_f32 v[14:15], v[14:15], v[80:81] op_sel_hi:[1,0]
	v_pk_mul_f32 v[12:13], v[12:13], v[80:81] op_sel_hi:[1,0]
	v_mfma_f32_16x16x32_bf16 v[20:23], v[128:131], v[178:181], v[20:23]
	v_mul_f32_e64 v10, v10, v80
	v_mul_f32_e64 v11, v11, v80
	v_pk_mul_f32 v[8:9], v[8:9], v[80:81] op_sel_hi:[1,0]
	v_pk_mul_f32 v[6:7], v[6:7], v[80:81] op_sel_hi:[1,0]
	v_mfma_f32_16x16x32_bf16 v[16:19], v[200:203], v[178:181], v[16:19]
	v_mul_f32_e64 v4, v4, v80
	v_mul_f32_e64 v5, v5, v80
	v_pk_mul_f32 v[2:3], v[2:3], v[80:81] op_sel_hi:[1,0]
	v_pk_mul_f32 v[0:1], v[0:1], v[80:81] op_sel_hi:[1,0]
	v_mfma_f32_16x16x32_bf16 v[28:31], v[116:119], v[196:199], v[28:31]
	v_mfma_f32_16x16x32_bf16 v[24:27], v[124:127], v[196:199], v[24:27]
	v_mfma_f32_16x16x32_bf16 v[20:23], v[132:135], v[196:199], v[20:23]
	v_mfma_f32_16x16x32_bf16 v[16:19], v[204:207], v[196:199], v[16:19]
	ds_read_b128 v[48:51], v160 offset:49152
	ds_read_b128 v[52:55], v160 offset:51200
	ds_read_b128 v[112:115], v160 offset:53248
	ds_read_b128 v[116:119], v160 offset:54272
	ds_read_b128 v[120:123], v160 offset:55296
	ds_read_b128 v[124:127], v160 offset:56320
	s_waitcnt lgkmcnt(0)
	v_mfma_f32_16x16x32_bf16 v[60:63], v[48:51], v[178:181], v[104:107]
	s_cmp_lt_i32 s27, 4
	s_cselect_b64 s[8:9], -1, 0
	s_and_b64 s[8:9], s[76:77], s[8:9]
	v_mfma_f32_16x16x32_bf16 v[48:51], v[112:115], v[178:181], v[136:139]
	s_and_b64 vcc, exec, s[8:9]
	v_mfma_f32_16x16x32_bf16 v[12:15], v[144:147], v[178:181], v[12:15]
	v_mfma_f32_16x16x32_bf16 v[8:11], v[152:155], v[178:181], v[8:11]
	v_mfma_f32_16x16x32_bf16 v[4:7], v[162:165], v[178:181], v[4:7]
	v_mfma_f32_16x16x32_bf16 v[0:3], v[170:173], v[178:181], v[0:3]
	v_mfma_f32_16x16x32_bf16 v[56:59], v[52:55], v[178:181], v[108:111]
	v_mfma_f32_16x16x32_bf16 v[52:55], v[116:119], v[196:199], v[48:51]
	v_mfma_f32_16x16x32_bf16 v[48:51], v[120:123], v[178:181], v[140:143]
	v_mfma_f32_16x16x32_bf16 v[12:15], v[148:151], v[196:199], v[12:15]
	v_mfma_f32_16x16x32_bf16 v[8:11], v[156:159], v[196:199], v[8:11]
	v_mfma_f32_16x16x32_bf16 v[4:7], v[166:169], v[196:199], v[4:7]
	v_mfma_f32_16x16x32_bf16 v[0:3], v[174:177], v[196:199], v[0:3]
	v_mfma_f32_16x16x32_bf16 v[48:51], v[124:127], v[196:199], v[48:51]
	s_cbranch_vccnz .LBB0_574
; #define LAS __attribute__((address_space(3)))
; __device__ __forceinline__ unsigned pk2(float lo, float hi) { return __builtin_bit_cast(unsigned, __builtin_convertvector((f32x2p){lo, hi}, bf16x2p)); }
; __device__ __forceinline__ void gdn_scan_phase(const Frame& F0, const Args& a0, int nblk, bool last) {
;     ...
;         if (!(last && c < 4)) {
;             LAS unsigned char* ob = ost + (s & 1) * 16384;
;             const bool ev = !(cc & 1);
; #pragma unroll
;             for (int mt = 0; mt < 4; ++mt) {
;                 const float s0 = ev ? O[mt][2] : O[mt][0], s1 = ev ? O[mt][3] : O[mt][1];
;                 const float r0 = __builtin_bit_cast(float, __builtin_amdgcn_mov_dpp(__builtin_bit_cast(int, s0), 0xB1, 0xF, 0xF, true));
;                 const float r1 = __builtin_bit_cast(float, __builtin_amdgcn_mov_dpp(__builtin_bit_cast(int, s1), 0xB1, 0xF, 0xF, true));
;                 const unsigned w0 = ev ? pk2(O[mt][0], r0) : pk2(r0, O[mt][2]), w1 = ev ? pk2(O[mt][1], r1) : pk2(r1, O[mt][3]);
; #pragma unroll
;                 for (int e = 0; e < 2; ++e) { const int p = 16 * mt + 4 * g + (ev ? 0 : 2) + e, tok = d ? 63 - p : p;
;                     *(LAS unsigned*)(ob + tok * 256 + (((2 * n + (cc >> 3)) ^ (((tok >> 2) & 3) << 2)) * 16) + (cc & 6) * 2) = e ? w1 : w0; } }
;         }
	s_lshl_b32 s6, s6, 14
	s_add_i32 s6, s6, 0
	v_cmp_eq_u32_e32 vcc, 1, v68
	s_add_i32 s36, s6, 0x1c000
	v_cmp_eq_u32_e64 s[6:7], 2, v68
	v_cndmask_b32_e32 v80, v60, v61, vcc
	v_cmp_eq_u32_e64 s[8:9], 3, v68
	v_cndmask_b32_e64 v80, v80, v62, s[6:7]
	v_cmp_eq_u32_e64 s[10:11], 1, v66
	v_cndmask_b32_e64 v80, v80, v63, s[8:9]
	v_cmp_eq_u32_e64 s[14:15], 2, v66
	v_cndmask_b32_e64 v104, v60, v61, s[10:11]
	v_mov_b32_dpp v80, v80 quad_perm:[1,0,3,2] row_mask:0xf bank_mask:0xf bound_ctrl:1
	v_cndmask_b32_e64 v104, v104, v62, s[14:15]
	v_cmp_eq_u32_e64 s[16:17], 3, v66
	v_cndmask_b32_e64 v60, v80, v60, s[2:3]
	v_cndmask_b32_e64 v62, v62, v80, s[2:3]
	v_cndmask_b32_e64 v104, v104, v63, s[16:17]
	v_cvt_pk_bf16_f32 v60, v60, v62
	v_add_u32_e32 v62, s36, v97
	v_mov_b32_dpp v104, v104 quad_perm:[1,0,3,2] row_mask:0xf bank_mask:0xf bound_ctrl:1
	v_cndmask_b32_e64 v61, v104, v61, s[2:3]
	v_cndmask_b32_e64 v63, v63, v104, s[2:3]
	v_add3_u32 v62, v62, v98, v84
	ds_write_b32 v62, v60
	v_cvt_pk_bf16_f32 v60, v61, v63
	v_add_u32_e32 v61, s36, v99
	v_add3_u32 v61, v61, v100, v84
	ds_write_b32 v61, v60
	v_cndmask_b32_e32 v60, v56, v57, vcc
	v_cndmask_b32_e64 v60, v60, v58, s[6:7]
	v_cndmask_b32_e64 v60, v60, v59, s[8:9]
	v_cndmask_b32_e64 v61, v56, v57, s[10:11]
	v_cndmask_b32_e64 v61, v61, v58, s[14:15]
	v_mov_b32_dpp v60, v60 quad_perm:[1,0,3,2] row_mask:0xf bank_mask:0xf bound_ctrl:1
	v_cndmask_b32_e64 v61, v61, v59, s[16:17]
	v_cndmask_b32_e64 v56, v60, v56, s[2:3]
	v_cndmask_b32_e64 v58, v58, v60, s[2:3]
	v_mov_b32_dpp v61, v61 quad_perm:[1,0,3,2] row_mask:0xf bank_mask:0xf bound_ctrl:1
	v_cvt_pk_bf16_f32 v56, v56, v58
	v_add_u32_e32 v58, s36, v93
	v_cndmask_b32_e64 v57, v61, v57, s[2:3]
	v_cndmask_b32_e64 v59, v59, v61, s[2:3]
	v_add3_u32 v58, v58, v94, v84
	ds_write_b32 v58, v56
	v_cvt_pk_bf16_f32 v56, v57, v59
	v_add_u32_e32 v57, s36, v95
	v_add3_u32 v57, v57, v96, v84
	ds_write_b32 v57, v56
	v_cndmask_b32_e32 v56, v52, v53, vcc
	v_cndmask_b32_e64 v56, v56, v54, s[6:7]
	v_cndmask_b32_e64 v56, v56, v55, s[8:9]
	v_cndmask_b32_e64 v57, v52, v53, s[10:11]
	v_cndmask_b32_e64 v57, v57, v54, s[14:15]
	v_mov_b32_dpp v56, v56 quad_perm:[1,0,3,2] row_mask:0xf bank_mask:0xf bound_ctrl:1
	v_cndmask_b32_e64 v57, v57, v55, s[16:17]
	v_cndmask_b32_e64 v52, v56, v52, s[2:3]
	v_cndmask_b32_e64 v54, v54, v56, s[2:3]
	v_mov_b32_dpp v57, v57 quad_perm:[1,0,3,2] row_mask:0xf bank_mask:0xf bound_ctrl:1
	v_cvt_pk_bf16_f32 v52, v52, v54
	v_add_u32_e32 v54, s36, v89
	v_cndmask_b32_e64 v53, v57, v53, s[2:3]
	v_cndmask_b32_e64 v55, v55, v57, s[2:3]
	v_add3_u32 v54, v54, v90, v84
	ds_write_b32 v54, v52
	v_cvt_pk_bf16_f32 v52, v53, v55
	v_add_u32_e32 v53, s36, v91
	v_add3_u32 v53, v53, v92, v84
	ds_write_b32 v53, v52
	v_cndmask_b32_e32 v52, v48, v49, vcc
	v_cndmask_b32_e64 v52, v52, v50, s[6:7]
	v_cndmask_b32_e64 v52, v52, v51, s[8:9]
	v_cndmask_b32_e64 v53, v48, v49, s[10:11]
	v_cndmask_b32_e64 v53, v53, v50, s[14:15]
	v_mov_b32_dpp v52, v52 quad_perm:[1,0,3,2] row_mask:0xf bank_mask:0xf bound_ctrl:1
	v_cndmask_b32_e64 v53, v53, v51, s[16:17]
	v_cndmask_b32_e64 v48, v52, v48, s[2:3]
	v_cndmask_b32_e64 v50, v50, v52, s[2:3]
	v_mov_b32_dpp v53, v53 quad_perm:[1,0,3,2] row_mask:0xf bank_mask:0xf bound_ctrl:1
	v_cvt_pk_bf16_f32 v48, v48, v50
	v_add_u32_e32 v50, s36, v85
	v_cndmask_b32_e64 v49, v53, v49, s[2:3]
	v_cndmask_b32_e64 v51, v51, v53, s[2:3]
	v_add3_u32 v50, v50, v86, v84
	ds_write_b32 v50, v48
	v_cvt_pk_bf16_f32 v48, v49, v51
	v_add_u32_e32 v49, s36, v87
	v_add3_u32 v49, v49, v88, v84
	ds_write_b32 v49, v48
